# retention state scan: all 32 loads of a batch in flight before the dependent chain
# speedup vs baseline: 1.0143x; 1.0139x over previous
; __device__ __forceinline__ float log2_gamma(int h) { return log2f(1.0f - exp2f(-5.0f - (float)h)); }
; __device__ __forceinline__ void run_phase(const Args& a, const int ph, LAS unsigned char* lds, const int tid, const int rpt) {
;     ...
;                     for (int idx = blockIdx.x * 512 + tid; idx < 12 * 4096; idx += nscan * 512) { const int bh = idx >> 12, el = idx & 4095, h = bh % 6;
;                         const float g64 = exp2f(64.f * log2_gamma(h)); const float* p = kvbuf + (size_t)bh * NCHUNK * 4096 + el; float* pd = (float*)(ws + WS_RPREV) + (size_t)bh * NCHUNK * 4096 + el; float rr = 0.f;
;                         for (int n = 0; n < NCHUNK; n += 32) { float t[32];
; #pragma unroll
;                             for (int i = 0; i < 32; ++i) t[i] = p[(size_t)(n + i) * 4096];
; #pragma unroll
;                             for (int i = 0; i < 32; ++i) { pd[(size_t)(n + i) * 4096] = rr; rr = g64 * rr + t[i]; } } }
.LBB0_184:
	s_add_i32 s15, s15, 32
	s_mov_b64 s[22:23], 0x80000
	v_add_co_u32_e32 v6, vcc, 0xe8f84000, v0
	s_nop 0
	v_addc_co_u32_e32 v7, vcc, -1, v1, vcc
	global_load_dword v8, v[6:7], off
	v_add_co_u32_e32 v6, vcc, 0xe8f88000, v0
	s_nop 0
	v_addc_co_u32_e32 v7, vcc, -1, v1, vcc
	global_load_dword v9, v[6:7], off
	v_add_co_u32_e32 v6, vcc, 0xe8f8c000, v0
	s_nop 0
	v_addc_co_u32_e32 v7, vcc, -1, v1, vcc
	global_load_dword v10, v[6:7], off
	v_add_co_u32_e32 v6, vcc, 0xe8f90000, v0
	s_nop 0
	v_addc_co_u32_e32 v7, vcc, -1, v1, vcc
	global_load_dword v11, v[6:7], off
	v_add_co_u32_e32 v6, vcc, 0xe8f94000, v0
	s_nop 0
	v_addc_co_u32_e32 v7, vcc, -1, v1, vcc
	global_load_dword v12, v[6:7], off
	v_add_co_u32_e32 v6, vcc, 0xe8f98000, v0
	s_nop 0
	v_addc_co_u32_e32 v7, vcc, -1, v1, vcc
	global_load_dword v13, v[6:7], off
	v_add_co_u32_e32 v6, vcc, 0xe8f9c000, v0
	s_nop 0
	v_addc_co_u32_e32 v7, vcc, -1, v1, vcc
	global_load_dword v14, v[6:7], off
	v_add_co_u32_e32 v6, vcc, 0xe8fa0000, v0
	s_nop 0
	v_addc_co_u32_e32 v7, vcc, -1, v1, vcc
	global_load_dword v15, v[6:7], off
	v_add_co_u32_e32 v6, vcc, 0xe8fa4000, v0
	s_nop 0
	v_addc_co_u32_e32 v7, vcc, -1, v1, vcc
	global_load_dword v16, v[6:7], off
	v_add_co_u32_e32 v6, vcc, 0xe8fa8000, v0
	s_nop 0
	v_addc_co_u32_e32 v7, vcc, -1, v1, vcc
	global_load_dword v17, v[6:7], off
	v_add_co_u32_e32 v6, vcc, 0xe8fac000, v0
	s_nop 0
	v_addc_co_u32_e32 v7, vcc, -1, v1, vcc
	global_load_dword v18, v[6:7], off
	v_add_co_u32_e32 v6, vcc, 0xe8fb0000, v0
	s_nop 0
	v_addc_co_u32_e32 v7, vcc, -1, v1, vcc
	global_load_dword v19, v[6:7], off
	v_add_co_u32_e32 v6, vcc, 0xe8fb4000, v0
	s_nop 0
	v_addc_co_u32_e32 v7, vcc, -1, v1, vcc
	global_load_dword v20, v[6:7], off
	v_add_co_u32_e32 v6, vcc, 0xe8fb8000, v0
	s_nop 0
	v_addc_co_u32_e32 v7, vcc, -1, v1, vcc
	global_load_dword v21, v[6:7], off
	v_add_co_u32_e32 v6, vcc, 0xe8fbc000, v0
	s_nop 0
	v_addc_co_u32_e32 v7, vcc, -1, v1, vcc
	global_load_dword v22, v[6:7], off
	v_add_co_u32_e32 v6, vcc, 0xe8fc0000, v0
	s_nop 0
	v_addc_co_u32_e32 v7, vcc, -1, v1, vcc
	global_load_dword v23, v[6:7], off
	v_add_co_u32_e32 v6, vcc, 0xe8fc4000, v0
	s_nop 0
	v_addc_co_u32_e32 v7, vcc, -1, v1, vcc
	global_load_dword v24, v[6:7], off
	v_add_co_u32_e32 v6, vcc, 0xe8fc8000, v0
	s_nop 0
	v_addc_co_u32_e32 v7, vcc, -1, v1, vcc
	global_load_dword v25, v[6:7], off
	v_add_co_u32_e32 v6, vcc, 0xe8fcc000, v0
	s_nop 0
	v_addc_co_u32_e32 v7, vcc, -1, v1, vcc
	global_load_dword v26, v[6:7], off
	v_add_co_u32_e32 v6, vcc, 0xe8fd0000, v0
	s_nop 0
	v_addc_co_u32_e32 v7, vcc, -1, v1, vcc
	global_load_dword v27, v[6:7], off
	v_add_co_u32_e32 v6, vcc, 0xe8fd4000, v0
	s_nop 0
	v_addc_co_u32_e32 v7, vcc, -1, v1, vcc
	global_load_dword v28, v[6:7], off
	v_add_co_u32_e32 v6, vcc, 0xe8fd8000, v0
	s_nop 0
	v_addc_co_u32_e32 v7, vcc, -1, v1, vcc
	global_load_dword v29, v[6:7], off
	v_add_co_u32_e32 v6, vcc, 0xe8fdc000, v0
	s_nop 0
	v_addc_co_u32_e32 v7, vcc, -1, v1, vcc
	global_load_dword v30, v[6:7], off
	v_add_co_u32_e32 v6, vcc, 0xe8fe0000, v0
	s_nop 0
	v_addc_co_u32_e32 v7, vcc, -1, v1, vcc
	global_load_dword v31, v[6:7], off
	v_add_co_u32_e32 v6, vcc, 0xe8fe4000, v0
	s_nop 0
	v_addc_co_u32_e32 v7, vcc, -1, v1, vcc
	global_load_dword v32, v[6:7], off
	v_add_co_u32_e32 v6, vcc, 0xe8fe8000, v0
	s_nop 0
	v_addc_co_u32_e32 v7, vcc, -1, v1, vcc
	global_load_dword v34, v[6:7], off
	v_add_co_u32_e32 v6, vcc, 0xe8fec000, v0
	s_nop 0
	v_addc_co_u32_e32 v7, vcc, -1, v1, vcc
	global_load_dword v35, v[6:7], off
	v_add_co_u32_e32 v6, vcc, 0xe8ff0000, v0
	s_nop 0
	v_addc_co_u32_e32 v7, vcc, -1, v1, vcc
	global_load_dword v36, v[6:7], off
	v_add_co_u32_e32 v6, vcc, 0xe8ff4000, v0
	s_nop 0
	v_addc_co_u32_e32 v7, vcc, -1, v1, vcc
	global_load_dword v37, v[6:7], off
	v_add_co_u32_e32 v6, vcc, 0xe8ff8000, v0
	s_nop 0
	v_addc_co_u32_e32 v7, vcc, -1, v1, vcc
	global_load_dword v39, v[6:7], off
	v_add_co_u32_e32 v6, vcc, 0xe8ffc000, v0
	s_nop 0
	v_addc_co_u32_e32 v7, vcc, -1, v1, vcc
	global_load_dword v40, v[6:7], off
	v_add_co_u32_e32 v6, vcc, 0xe9000000, v0
	s_nop 0
	v_addc_co_u32_e32 v7, vcc, -1, v1, vcc
	global_load_dword v41, v[6:7], off
	s_waitcnt vmcnt(0)
; __device__ __forceinline__ void run_phase(const Args& a, const int ph, LAS unsigned char* lds, const int tid, const int rpt) {
;     ...
;                         for (int n = 0; n < NCHUNK; n += 32) { float t[32];
; #pragma unroll
;                             for (int i = 0; i < 32; ++i) t[i] = p[(size_t)(n + i) * 4096];
; #pragma unroll
;                             for (int i = 0; i < 32; ++i) { pd[(size_t)(n + i) * 4096] = rr; rr = g64 * rr + t[i]; } } }
	v_fmac_f32_e32 v8, v4, v5
	v_fmac_f32_e32 v9, v4, v8
	v_fmac_f32_e32 v10, v4, v9
	v_fmac_f32_e32 v11, v4, v10
	v_fmac_f32_e32 v12, v4, v11
	v_fmac_f32_e32 v13, v4, v12
	v_fmac_f32_e32 v14, v4, v13
	v_fmac_f32_e32 v15, v4, v14
	v_fmac_f32_e32 v16, v4, v15
	v_fmac_f32_e32 v17, v4, v16
	v_fmac_f32_e32 v18, v4, v17
	v_fmac_f32_e32 v19, v4, v18
	v_fmac_f32_e32 v20, v4, v19
	v_fmac_f32_e32 v21, v4, v20
	v_fmac_f32_e32 v22, v4, v21
	v_fmac_f32_e32 v23, v4, v22
	v_fmac_f32_e32 v24, v4, v23
	v_fmac_f32_e32 v25, v4, v24
	v_fmac_f32_e32 v26, v4, v25
	v_fmac_f32_e32 v27, v4, v26
	v_fmac_f32_e32 v28, v4, v27
	v_fmac_f32_e32 v29, v4, v28
	v_fmac_f32_e32 v30, v4, v29
	v_fmac_f32_e32 v31, v4, v30
	v_fmac_f32_e32 v32, v4, v31
	v_fmac_f32_e32 v34, v4, v32
	v_fmac_f32_e32 v35, v4, v34
	v_fmac_f32_e32 v36, v4, v35
	v_fmac_f32_e32 v37, v4, v36
	v_fmac_f32_e32 v39, v4, v37
	v_fmac_f32_e32 v40, v4, v39
	v_fmac_f32_e32 v41, v4, v40
	v_add_co_u32_e32 v6, vcc, 0xfff84000, v0
	s_nop 0
	v_addc_co_u32_e32 v7, vcc, -1, v1, vcc
	s_nop 0
	global_store_dword v[6:7], v5, off
	v_add_co_u32_e32 v6, vcc, 0xfff88000, v0
	s_nop 0
	v_addc_co_u32_e32 v7, vcc, -1, v1, vcc
	s_nop 0
	global_store_dword v[6:7], v8, off
	v_add_co_u32_e32 v6, vcc, 0xfff8c000, v0
	s_nop 0
	v_addc_co_u32_e32 v7, vcc, -1, v1, vcc
	s_nop 0
	global_store_dword v[6:7], v9, off
	global_store_dword v[0:1], v40, off
	v_add_co_u32_e32 v6, vcc, 0xfff90000, v0
	s_nop 0
	v_addc_co_u32_e32 v7, vcc, -1, v1, vcc
	s_nop 0
	global_store_dword v[6:7], v10, off
	v_add_co_u32_e32 v6, vcc, 0xfff94000, v0
	s_nop 0
	v_addc_co_u32_e32 v7, vcc, -1, v1, vcc
	s_nop 0
	global_store_dword v[6:7], v11, off
	v_add_co_u32_e32 v6, vcc, 0xfff98000, v0
	s_nop 0
	v_addc_co_u32_e32 v7, vcc, -1, v1, vcc
	s_nop 0
	global_store_dword v[6:7], v12, off
	v_add_co_u32_e32 v6, vcc, 0xfff9c000, v0
	s_nop 0
	v_addc_co_u32_e32 v7, vcc, -1, v1, vcc
	s_nop 0
	global_store_dword v[6:7], v13, off
	v_add_co_u32_e32 v6, vcc, 0xfffa0000, v0
	s_nop 0
	v_addc_co_u32_e32 v7, vcc, -1, v1, vcc
	s_nop 0
	global_store_dword v[6:7], v14, off
	v_add_co_u32_e32 v6, vcc, 0xfffa4000, v0
	s_nop 0
	v_addc_co_u32_e32 v7, vcc, -1, v1, vcc
	s_nop 0
	global_store_dword v[6:7], v15, off
	v_add_co_u32_e32 v6, vcc, 0xfffa8000, v0
	s_nop 0
	v_addc_co_u32_e32 v7, vcc, -1, v1, vcc
	s_nop 0
	global_store_dword v[6:7], v16, off
	v_add_co_u32_e32 v6, vcc, 0xfffac000, v0
	s_nop 0
	v_addc_co_u32_e32 v7, vcc, -1, v1, vcc
	s_nop 0
	global_store_dword v[6:7], v17, off
	v_add_co_u32_e32 v6, vcc, 0xfffb0000, v0
	s_nop 0
	v_addc_co_u32_e32 v7, vcc, -1, v1, vcc
	s_nop 0
	global_store_dword v[6:7], v18, off
	v_add_co_u32_e32 v6, vcc, 0xfffb4000, v0
	s_nop 0
	v_addc_co_u32_e32 v7, vcc, -1, v1, vcc
	s_nop 0
	global_store_dword v[6:7], v19, off
	v_add_co_u32_e32 v6, vcc, 0xfffb8000, v0
	s_nop 0
	v_addc_co_u32_e32 v7, vcc, -1, v1, vcc
	s_nop 0
	global_store_dword v[6:7], v20, off
	v_add_co_u32_e32 v6, vcc, 0xfffbc000, v0
	s_nop 0
	v_addc_co_u32_e32 v7, vcc, -1, v1, vcc
	s_nop 0
	global_store_dword v[6:7], v21, off
	v_add_co_u32_e32 v6, vcc, 0xfffc0000, v0
	s_nop 0
	v_addc_co_u32_e32 v7, vcc, -1, v1, vcc
	s_nop 0
	global_store_dword v[6:7], v22, off
	v_add_co_u32_e32 v6, vcc, 0xfffc4000, v0
	s_nop 0
	v_addc_co_u32_e32 v7, vcc, -1, v1, vcc
	s_nop 0
	global_store_dword v[6:7], v23, off
	v_add_co_u32_e32 v6, vcc, 0xfffc8000, v0
	s_nop 0
	v_addc_co_u32_e32 v7, vcc, -1, v1, vcc
	s_nop 0
	global_store_dword v[6:7], v24, off
	v_add_co_u32_e32 v6, vcc, 0xfffcc000, v0
	s_nop 0
	v_addc_co_u32_e32 v7, vcc, -1, v1, vcc
	s_nop 0
	global_store_dword v[6:7], v25, off
	v_add_co_u32_e32 v6, vcc, 0xfffd0000, v0
	s_nop 0
	v_addc_co_u32_e32 v7, vcc, -1, v1, vcc
	s_nop 0
	global_store_dword v[6:7], v26, off
	v_add_co_u32_e32 v6, vcc, 0xfffd4000, v0
	s_nop 0
	v_addc_co_u32_e32 v7, vcc, -1, v1, vcc
	s_nop 0
	global_store_dword v[6:7], v27, off
	v_add_co_u32_e32 v6, vcc, 0xfffd8000, v0
	s_nop 0
	v_addc_co_u32_e32 v7, vcc, -1, v1, vcc
	s_nop 0
	global_store_dword v[6:7], v28, off
	v_add_co_u32_e32 v6, vcc, 0xfffdc000, v0
	s_nop 0
	v_addc_co_u32_e32 v7, vcc, -1, v1, vcc
	s_nop 0
	global_store_dword v[6:7], v29, off
	v_add_co_u32_e32 v6, vcc, 0xfffe0000, v0
	s_nop 0
	v_addc_co_u32_e32 v7, vcc, -1, v1, vcc
	s_nop 0
	global_store_dword v[6:7], v30, off
	v_add_co_u32_e32 v6, vcc, 0xfffe4000, v0
	s_nop 0
	v_addc_co_u32_e32 v7, vcc, -1, v1, vcc
	s_nop 0
	global_store_dword v[6:7], v31, off
	v_add_co_u32_e32 v6, vcc, 0xfffe8000, v0
	s_nop 0
	v_addc_co_u32_e32 v7, vcc, -1, v1, vcc
	s_nop 0
	global_store_dword v[6:7], v32, off
	v_add_co_u32_e32 v6, vcc, 0xfffec000, v0
	s_nop 0
	v_addc_co_u32_e32 v7, vcc, -1, v1, vcc
	s_nop 0
	global_store_dword v[6:7], v34, off
	v_add_co_u32_e32 v6, vcc, 0xffff0000, v0
	s_nop 0
	v_addc_co_u32_e32 v7, vcc, -1, v1, vcc
	s_nop 0
	global_store_dword v[6:7], v35, off
	v_add_co_u32_e32 v6, vcc, 0xffff4000, v0
	s_nop 0
	v_addc_co_u32_e32 v7, vcc, -1, v1, vcc
	s_nop 0
	global_store_dword v[6:7], v36, off
	v_add_co_u32_e32 v6, vcc, 0xffff8000, v0
	s_nop 0
	v_addc_co_u32_e32 v7, vcc, -1, v1, vcc
	s_nop 0
	global_store_dword v[6:7], v37, off
	v_add_co_u32_e32 v6, vcc, 0xffffc000, v0
	s_nop 0
	v_addc_co_u32_e32 v7, vcc, -1, v1, vcc
	s_nop 0
	global_store_dword v[6:7], v39, off
	v_mov_b32_e32 v5, v41
	v_lshl_add_u64 v[0:1], v[0:1], 0, s[22:23]
	s_cmpk_gt_u32 s15, 0xdf
	s_cbranch_scc0 .LBB0_184
	v_add_u32_e32 v2, s12, v2
	s_mov_b32 s15, 0xbfff
	v_cmp_lt_i32_e32 vcc, s15, v2
	s_or_b64 s[20:21], vcc, s[20:21]
	v_add_u16_e32 v3, s12, v3
	s_andn2_b64 exec, exec, s[20:21]
	s_cbranch_execnz .LBB0_183
